# MFMA issue order within each 8-group changed to Gray order (one operand changes per step)
# baseline (speedup 1.0000x reference)
.LBB0_300:
	s_add_u32 s42, s40, 0xfffc0080
	s_addc_u32 s43, s41, -1
	s_add_i32 s86, 0, 0x10000
	s_cmp_eq_u32 s85, 12
	s_cselect_b32 s45, s20, s43
	s_cselect_b32 s44, s25, s42
	s_cselect_b32 s43, s23, s84
	s_cselect_b32 s42, s82, s83
	s_add_i32 s87, 0, 0x14000
	v_add_u32_e32 v92, s86, v173
	v_add_u32_e32 v170, s87, v173
	ds_read_b128 v[72:75], v92
	ds_read_b128 v[76:79], v92 offset:1024
	ds_read_b128 v[88:91], v92 offset:2048
	ds_read_b128 v[92:95], v92 offset:3072
	ds_read_b128 v[162:165], v170
	ds_read_b128 v[166:169], v170 offset:1024
	ds_read_b128 v[178:181], v170 offset:2048
	ds_read_b128 v[182:185], v170 offset:3072
	v_lshl_add_u64 v[170:171], s[40:41], 0, v[160:161]
	s_add_i32 m0, s39, 0xc000
	ds_read_b128 v[186:189], v176
	ds_read_b128 v[190:193], v176 offset:1024
	ds_read_b128 v[210:213], v176 offset:2048
	ds_read_b128 v[214:217], v176 offset:3072
	ds_read_b128 v[218:221], v176 offset:4096
	ds_read_b128 v[222:225], v176 offset:5120
	ds_read_b128 v[226:229], v176 offset:6144
	ds_read_b128 v[230:233], v176 offset:7168
	global_load_lds_dwordx4 v[170:171], off
	v_lshl_add_u64 v[170:171], s[40:41], 0, v[158:159]
	s_add_i32 m0, s39, 0xe000
	s_nop 0
	global_load_lds_dwordx4 v[170:171], off
	s_waitcnt vmcnt(8)
	s_waitcnt lgkmcnt(0)
	s_barrier
	s_setprio 1
	s_waitcnt lgkmcnt(0)
	v_mfma_f32_16x16x32_bf16 v[140:143], v[72:75], v[186:189], v[140:143]
	v_mfma_f32_16x16x32_bf16 v[136:139], v[88:91], v[186:189], v[136:139]
	v_mfma_f32_16x16x32_bf16 v[116:119], v[88:91], v[210:213], v[116:119]
	v_mfma_f32_16x16x32_bf16 v[124:127], v[72:75], v[210:213], v[124:127]
	v_mfma_f32_16x16x32_bf16 v[108:111], v[72:75], v[218:221], v[108:111]
	v_mfma_f32_16x16x32_bf16 v[100:103], v[88:91], v[218:221], v[100:103]
	v_mfma_f32_16x16x32_bf16 v[68:71], v[88:91], v[226:229], v[68:71]
	v_mfma_f32_16x16x32_bf16 v[84:87], v[72:75], v[226:229], v[84:87]
	v_mfma_f32_16x16x32_bf16 v[140:143], v[76:79], v[190:193], v[140:143]
	v_mfma_f32_16x16x32_bf16 v[136:139], v[92:95], v[190:193], v[136:139]
	v_mfma_f32_16x16x32_bf16 v[116:119], v[92:95], v[214:217], v[116:119]
	v_mfma_f32_16x16x32_bf16 v[124:127], v[76:79], v[214:217], v[124:127]
	v_mfma_f32_16x16x32_bf16 v[108:111], v[76:79], v[222:225], v[108:111]
	v_mfma_f32_16x16x32_bf16 v[100:103], v[92:95], v[222:225], v[100:103]
	v_mfma_f32_16x16x32_bf16 v[68:71], v[92:95], v[230:233], v[68:71]
	v_mfma_f32_16x16x32_bf16 v[84:87], v[76:79], v[230:233], v[84:87]
	s_setprio 0
	s_setprio 1
	v_mfma_f32_16x16x32_bf16 v[132:135], v[162:165], v[186:189], v[132:135]
	v_mfma_f32_16x16x32_bf16 v[128:131], v[178:181], v[186:189], v[128:131]
	v_mfma_f32_16x16x32_bf16 v[112:115], v[178:181], v[210:213], v[112:115]
	v_mfma_f32_16x16x32_bf16 v[120:123], v[162:165], v[210:213], v[120:123]
	v_mfma_f32_16x16x32_bf16 v[104:107], v[162:165], v[218:221], v[104:107]
	v_mfma_f32_16x16x32_bf16 v[96:99], v[178:181], v[218:221], v[96:99]
	v_mfma_f32_16x16x32_bf16 v[64:67], v[178:181], v[226:229], v[64:67]
	v_mfma_f32_16x16x32_bf16 v[80:83], v[162:165], v[226:229], v[80:83]
	v_mfma_f32_16x16x32_bf16 v[132:135], v[166:169], v[190:193], v[132:135]
	v_mfma_f32_16x16x32_bf16 v[128:131], v[182:185], v[190:193], v[128:131]
	v_mfma_f32_16x16x32_bf16 v[112:115], v[182:185], v[214:217], v[112:115]
	v_mfma_f32_16x16x32_bf16 v[120:123], v[166:169], v[214:217], v[120:123]
	v_mfma_f32_16x16x32_bf16 v[104:107], v[166:169], v[222:225], v[104:107]
	v_mfma_f32_16x16x32_bf16 v[96:99], v[182:185], v[222:225], v[96:99]
	v_mfma_f32_16x16x32_bf16 v[64:67], v[182:185], v[230:233], v[64:67]
	v_mfma_f32_16x16x32_bf16 v[80:83], v[166:169], v[230:233], v[80:83]
	s_setprio 0
	s_barrier
	s_add_i32 s86, s86, s70
	v_lshl_add_u64 v[170:171], s[42:43], 0, v[150:151]
	s_mov_b32 m0, s86
	ds_read_b128 v[186:189], v176 offset:16384
	ds_read_b128 v[190:193], v176 offset:17408
	ds_read_b128 v[210:213], v176 offset:18432
	ds_read_b128 v[214:217], v176 offset:19456
	ds_read_b128 v[218:221], v176 offset:20480
	ds_read_b128 v[222:225], v176 offset:21504
	ds_read_b128 v[226:229], v176 offset:22528
	ds_read_b128 v[230:233], v176 offset:23552
	global_load_lds_dwordx4 v[170:171], off
	s_add_i32 m0, s86, 0x2000
	s_add_u32 vcc_lo, s42, 0x40000
	v_lshl_add_u64 v[234:235], s[42:43], 0, v[156:157]
	s_addc_u32 vcc_hi, s43, 0
	s_add_i32 s86, s87, s70
	global_load_lds_dwordx4 v[234:235], off
	v_lshl_add_u64 v[236:237], vcc, 0, v[150:151]
	s_mov_b32 m0, s86
	v_lshl_add_u64 v[238:239], s[44:45], 0, v[154:155]
	global_load_lds_dwordx4 v[236:237], off
	v_lshl_add_u64 v[236:237], vcc, 0, v[156:157]
	s_add_i32 m0, s86, 0x2000
	s_nop 0
	global_load_lds_dwordx4 v[236:237], off
	v_lshl_add_u64 v[236:237], s[44:45], 0, v[152:153]
	s_mov_b32 m0, s39
	s_nop 0
	global_load_lds_dwordx4 v[236:237], off
	s_mov_b32 m0, s71
	s_nop 0
	global_load_lds_dwordx4 v[238:239], off
	s_waitcnt vmcnt(8)
	s_waitcnt lgkmcnt(0)
	s_barrier
	s_setprio 1
	s_waitcnt lgkmcnt(0)
	v_mfma_f32_16x16x32_bf16 v[60:63], v[72:75], v[186:189], v[60:63]
	v_mfma_f32_16x16x32_bf16 v[52:55], v[88:91], v[186:189], v[52:55]
	v_mfma_f32_16x16x32_bf16 v[36:39], v[88:91], v[210:213], v[36:39]
	v_mfma_f32_16x16x32_bf16 v[44:47], v[72:75], v[210:213], v[44:47]
	v_mfma_f32_16x16x32_bf16 v[28:31], v[72:75], v[218:221], v[28:31]
	v_mfma_f32_16x16x32_bf16 v[20:23], v[88:91], v[218:221], v[20:23]
	v_mfma_f32_16x16x32_bf16 v[4:7], v[88:91], v[226:229], v[4:7]
	v_mfma_f32_16x16x32_bf16 v[12:15], v[72:75], v[226:229], v[12:15]
	v_mfma_f32_16x16x32_bf16 v[60:63], v[76:79], v[190:193], v[60:63]
	v_mfma_f32_16x16x32_bf16 v[52:55], v[92:95], v[190:193], v[52:55]
	v_mfma_f32_16x16x32_bf16 v[36:39], v[92:95], v[214:217], v[36:39]
	v_mfma_f32_16x16x32_bf16 v[44:47], v[76:79], v[214:217], v[44:47]
	v_mfma_f32_16x16x32_bf16 v[28:31], v[76:79], v[222:225], v[28:31]
	v_mfma_f32_16x16x32_bf16 v[20:23], v[92:95], v[222:225], v[20:23]
	v_mfma_f32_16x16x32_bf16 v[4:7], v[92:95], v[230:233], v[4:7]
	v_mfma_f32_16x16x32_bf16 v[12:15], v[76:79], v[230:233], v[12:15]
	s_setprio 0
	s_setprio 1
	v_mfma_f32_16x16x32_bf16 v[56:59], v[162:165], v[186:189], v[56:59]
	v_mfma_f32_16x16x32_bf16 v[48:51], v[178:181], v[186:189], v[48:51]
	v_mfma_f32_16x16x32_bf16 v[32:35], v[178:181], v[210:213], v[32:35]
	v_mfma_f32_16x16x32_bf16 v[40:43], v[162:165], v[210:213], v[40:43]
	v_mfma_f32_16x16x32_bf16 v[24:27], v[162:165], v[218:221], v[24:27]
	v_mfma_f32_16x16x32_bf16 v[16:19], v[178:181], v[218:221], v[16:19]
	v_mfma_f32_16x16x32_bf16 v[0:3], v[178:181], v[226:229], v[0:3]
	v_mfma_f32_16x16x32_bf16 v[8:11], v[162:165], v[226:229], v[8:11]
	v_mfma_f32_16x16x32_bf16 v[56:59], v[166:169], v[190:193], v[56:59]
	v_mfma_f32_16x16x32_bf16 v[48:51], v[182:185], v[190:193], v[48:51]
	v_mfma_f32_16x16x32_bf16 v[32:35], v[182:185], v[214:217], v[32:35]
	v_mfma_f32_16x16x32_bf16 v[40:43], v[166:169], v[214:217], v[40:43]
	v_mfma_f32_16x16x32_bf16 v[24:27], v[166:169], v[222:225], v[24:27]
	v_mfma_f32_16x16x32_bf16 v[16:19], v[182:185], v[222:225], v[16:19]
	v_mfma_f32_16x16x32_bf16 v[0:3], v[182:185], v[230:233], v[0:3]
	v_mfma_f32_16x16x32_bf16 v[8:11], v[166:169], v[230:233], v[8:11]
	s_setprio 0
	s_barrier
	s_add_i32 s86, 0, 0x18000
	s_add_i32 s87, 0, 0x1c000
	v_add_u32_e32 v92, s86, v173
	v_add_u32_e32 v182, s87, v173
	ds_read_b128 v[72:75], v92
	ds_read_b128 v[76:79], v92 offset:1024
	ds_read_b128 v[88:91], v92 offset:2048
	ds_read_b128 v[92:95], v92 offset:3072
	ds_read_b128 v[162:165], v182
	ds_read_b128 v[166:169], v182 offset:1024
	ds_read_b128 v[178:181], v182 offset:2048
	ds_read_b128 v[182:185], v182 offset:3072
	s_add_u32 s44, s44, 0x40000
	s_addc_u32 s45, s45, 0
	s_mov_b32 m0, s72
	v_lshl_add_u64 v[240:241], s[44:45], 0, v[152:153]
	ds_read_b128 v[186:189], v176 offset:32768
	ds_read_b128 v[190:193], v176 offset:33792
	ds_read_b128 v[210:213], v176 offset:34816
	ds_read_b128 v[214:217], v176 offset:35840
	ds_read_b128 v[218:221], v176 offset:36864
	ds_read_b128 v[222:225], v176 offset:37888
	ds_read_b128 v[226:229], v176 offset:38912
	ds_read_b128 v[230:233], v176 offset:39936
	global_load_lds_dwordx4 v[240:241], off
	v_lshl_add_u64 v[240:241], s[44:45], 0, v[154:155]
	s_mov_b32 m0, s73
	s_nop 0
	global_load_lds_dwordx4 v[240:241], off
	s_waitcnt vmcnt(8)
	s_waitcnt lgkmcnt(0)
	s_barrier
	s_setprio 1
	s_waitcnt lgkmcnt(0)
	v_mfma_f32_16x16x32_bf16 v[140:143], v[72:75], v[186:189], v[140:143]
	v_mfma_f32_16x16x32_bf16 v[136:139], v[88:91], v[186:189], v[136:139]
	v_mfma_f32_16x16x32_bf16 v[116:119], v[88:91], v[210:213], v[116:119]
	v_mfma_f32_16x16x32_bf16 v[124:127], v[72:75], v[210:213], v[124:127]
	v_mfma_f32_16x16x32_bf16 v[108:111], v[72:75], v[218:221], v[108:111]
	v_mfma_f32_16x16x32_bf16 v[100:103], v[88:91], v[218:221], v[100:103]
	v_mfma_f32_16x16x32_bf16 v[68:71], v[88:91], v[226:229], v[68:71]
	v_mfma_f32_16x16x32_bf16 v[84:87], v[72:75], v[226:229], v[84:87]
	v_mfma_f32_16x16x32_bf16 v[140:143], v[76:79], v[190:193], v[140:143]
	v_mfma_f32_16x16x32_bf16 v[136:139], v[92:95], v[190:193], v[136:139]
	v_mfma_f32_16x16x32_bf16 v[116:119], v[92:95], v[214:217], v[116:119]
	v_mfma_f32_16x16x32_bf16 v[124:127], v[76:79], v[214:217], v[124:127]
	v_mfma_f32_16x16x32_bf16 v[108:111], v[76:79], v[222:225], v[108:111]
	v_mfma_f32_16x16x32_bf16 v[100:103], v[92:95], v[222:225], v[100:103]
	v_mfma_f32_16x16x32_bf16 v[68:71], v[92:95], v[230:233], v[68:71]
	v_mfma_f32_16x16x32_bf16 v[84:87], v[76:79], v[230:233], v[84:87]
	s_setprio 0
	s_setprio 1
	v_mfma_f32_16x16x32_bf16 v[132:135], v[162:165], v[186:189], v[132:135]
	v_mfma_f32_16x16x32_bf16 v[128:131], v[178:181], v[186:189], v[128:131]
	v_mfma_f32_16x16x32_bf16 v[112:115], v[178:181], v[210:213], v[112:115]
	v_mfma_f32_16x16x32_bf16 v[120:123], v[162:165], v[210:213], v[120:123]
	v_mfma_f32_16x16x32_bf16 v[104:107], v[162:165], v[218:221], v[104:107]
	v_mfma_f32_16x16x32_bf16 v[96:99], v[178:181], v[218:221], v[96:99]
	v_mfma_f32_16x16x32_bf16 v[64:67], v[178:181], v[226:229], v[64:67]
	v_mfma_f32_16x16x32_bf16 v[80:83], v[162:165], v[226:229], v[80:83]
	v_mfma_f32_16x16x32_bf16 v[132:135], v[166:169], v[190:193], v[132:135]
	v_mfma_f32_16x16x32_bf16 v[128:131], v[182:185], v[190:193], v[128:131]
	v_mfma_f32_16x16x32_bf16 v[112:115], v[182:185], v[214:217], v[112:115]
	v_mfma_f32_16x16x32_bf16 v[120:123], v[166:169], v[214:217], v[120:123]
	v_mfma_f32_16x16x32_bf16 v[104:107], v[166:169], v[222:225], v[104:107]
	v_mfma_f32_16x16x32_bf16 v[96:99], v[182:185], v[222:225], v[96:99]
	v_mfma_f32_16x16x32_bf16 v[64:67], v[182:185], v[230:233], v[64:67]
	v_mfma_f32_16x16x32_bf16 v[80:83], v[166:169], v[230:233], v[80:83]
	s_setprio 0
	s_barrier
	s_add_i32 s44, s86, s70
	v_lshl_add_u64 v[170:171], v[170:171], 0, s[10:11]
	s_mov_b32 m0, s44
	ds_read_b128 v[186:189], v176 offset:49152
	ds_read_b128 v[190:193], v176 offset:50176
	ds_read_b128 v[210:213], v176 offset:51200
	ds_read_b128 v[214:217], v176 offset:52224
	ds_read_b128 v[218:221], v176 offset:53248
	ds_read_b128 v[222:225], v176 offset:54272
	ds_read_b128 v[226:229], v176 offset:55296
	ds_read_b128 v[230:233], v176 offset:56320
	global_load_lds_dwordx4 v[170:171], off
	s_add_i32 m0, s44, 0x2000
	s_add_u32 s42, s42, 0x40080
	v_lshl_add_u64 v[170:171], v[234:235], 0, s[10:11]
	s_addc_u32 s43, s43, 0
	s_add_i32 s44, s87, s70
	global_load_lds_dwordx4 v[170:171], off
	v_lshl_add_u64 v[170:171], s[42:43], 0, v[150:151]
	s_mov_b32 m0, s44
	s_nop 0
	global_load_lds_dwordx4 v[170:171], off
	v_lshl_add_u64 v[170:171], s[42:43], 0, v[156:157]
	s_add_i32 m0, s44, 0x2000
	s_nop 0
	global_load_lds_dwordx4 v[170:171], off
	v_lshl_add_u64 v[170:171], v[236:237], 0, s[10:11]
	s_mov_b32 m0, s74
	s_nop 0
	global_load_lds_dwordx4 v[170:171], off
	v_lshl_add_u64 v[170:171], v[238:239], 0, s[10:11]
	s_mov_b32 m0, s75
	s_nop 0
	global_load_lds_dwordx4 v[170:171], off
	s_waitcnt vmcnt(8)
	s_waitcnt lgkmcnt(0)
	s_barrier
	s_setprio 1
	s_waitcnt lgkmcnt(0)
	v_mfma_f32_16x16x32_bf16 v[60:63], v[72:75], v[186:189], v[60:63]
	v_mfma_f32_16x16x32_bf16 v[52:55], v[88:91], v[186:189], v[52:55]
	v_mfma_f32_16x16x32_bf16 v[36:39], v[88:91], v[210:213], v[36:39]
	v_mfma_f32_16x16x32_bf16 v[44:47], v[72:75], v[210:213], v[44:47]
	v_mfma_f32_16x16x32_bf16 v[28:31], v[72:75], v[218:221], v[28:31]
	v_mfma_f32_16x16x32_bf16 v[20:23], v[88:91], v[218:221], v[20:23]
	v_mfma_f32_16x16x32_bf16 v[4:7], v[88:91], v[226:229], v[4:7]
	v_mfma_f32_16x16x32_bf16 v[12:15], v[72:75], v[226:229], v[12:15]
	v_mfma_f32_16x16x32_bf16 v[60:63], v[76:79], v[190:193], v[60:63]
	v_mfma_f32_16x16x32_bf16 v[52:55], v[92:95], v[190:193], v[52:55]
	v_mfma_f32_16x16x32_bf16 v[36:39], v[92:95], v[214:217], v[36:39]
	v_mfma_f32_16x16x32_bf16 v[44:47], v[76:79], v[214:217], v[44:47]
	v_mfma_f32_16x16x32_bf16 v[28:31], v[76:79], v[222:225], v[28:31]
	v_mfma_f32_16x16x32_bf16 v[20:23], v[92:95], v[222:225], v[20:23]
	v_mfma_f32_16x16x32_bf16 v[4:7], v[92:95], v[230:233], v[4:7]
	v_mfma_f32_16x16x32_bf16 v[12:15], v[76:79], v[230:233], v[12:15]
	s_setprio 0
	s_setprio 1
	v_mfma_f32_16x16x32_bf16 v[56:59], v[162:165], v[186:189], v[56:59]
	v_mfma_f32_16x16x32_bf16 v[48:51], v[178:181], v[186:189], v[48:51]
	v_mfma_f32_16x16x32_bf16 v[32:35], v[178:181], v[210:213], v[32:35]
	v_mfma_f32_16x16x32_bf16 v[40:43], v[162:165], v[210:213], v[40:43]
	v_mfma_f32_16x16x32_bf16 v[24:27], v[162:165], v[218:221], v[24:27]
	v_mfma_f32_16x16x32_bf16 v[16:19], v[178:181], v[218:221], v[16:19]
	v_mfma_f32_16x16x32_bf16 v[0:3], v[178:181], v[226:229], v[0:3]
	v_mfma_f32_16x16x32_bf16 v[8:11], v[162:165], v[226:229], v[8:11]
	v_mfma_f32_16x16x32_bf16 v[56:59], v[166:169], v[190:193], v[56:59]
	v_mfma_f32_16x16x32_bf16 v[48:51], v[182:185], v[190:193], v[48:51]
	v_mfma_f32_16x16x32_bf16 v[32:35], v[182:185], v[214:217], v[32:35]
	v_mfma_f32_16x16x32_bf16 v[40:43], v[166:169], v[214:217], v[40:43]
	v_mfma_f32_16x16x32_bf16 v[24:27], v[166:169], v[222:225], v[24:27]
	v_mfma_f32_16x16x32_bf16 v[16:19], v[182:185], v[222:225], v[16:19]
	v_mfma_f32_16x16x32_bf16 v[0:3], v[182:185], v[230:233], v[0:3]
	v_mfma_f32_16x16x32_bf16 v[8:11], v[166:169], v[230:233], v[8:11]
	s_setprio 0
	s_barrier
	s_add_i32 s85, s85, 2
	s_add_u32 s83, s83, 0x100
	s_addc_u32 s84, s84, 0
	s_add_u32 s40, s40, 0x100
	s_addc_u32 s41, s41, 0
	s_cmp_gt_u32 s85, 13
	s_cbranch_scc0 .LBB0_300
	s_and_b64 vcc, exec, s[16:17]
	s_cbranch_vccz .LBB0_303
	s_barrier

.LBB0_339:
	s_add_u32 s40, s38, 0xfffc0080
	s_addc_u32 s41, s39, -1
	s_add_i32 s81, 0, 0x10000
	s_cmp_eq_u32 s80, 12
	s_cselect_b32 s43, s20, s41
	s_cselect_b32 s42, s23, s40
	s_cselect_b32 s41, s5, s79
	s_cselect_b32 s40, s77, s78
	s_add_i32 s84, 0, 0x14000
	v_add_u32_e32 v116, s81, v171
	v_add_u32_e32 v175, s84, v171
	ds_read_b128 v[96:99], v116
	ds_read_b128 v[108:111], v116 offset:1024
	ds_read_b128 v[112:115], v116 offset:2048
	ds_read_b128 v[116:119], v116 offset:3072
	ds_read_b128 v[162:165], v175
	ds_read_b128 v[166:169], v175 offset:1024
	ds_read_b128 v[176:179], v175 offset:2048
	ds_read_b128 v[180:183], v175 offset:3072
	v_lshl_add_u64 v[192:193], s[38:39], 0, v[160:161]
	s_add_i32 m0, s35, 0xc000
	ds_read_b128 v[184:187], v174
	ds_read_b128 v[188:191], v174 offset:1024
	ds_read_b128 v[210:213], v174 offset:2048
	ds_read_b128 v[214:217], v174 offset:3072
	ds_read_b128 v[218:221], v174 offset:4096
	ds_read_b128 v[222:225], v174 offset:5120
	ds_read_b128 v[226:229], v174 offset:6144
	ds_read_b128 v[230:233], v174 offset:7168
	global_load_lds_dwordx4 v[192:193], off
	v_lshl_add_u64 v[192:193], s[38:39], 0, v[158:159]
	s_add_i32 m0, s35, 0xe000
	s_nop 0
	global_load_lds_dwordx4 v[192:193], off
	s_waitcnt vmcnt(8)
	s_waitcnt lgkmcnt(0)
	s_barrier
	s_setprio 1
	s_waitcnt lgkmcnt(0)
	v_mfma_f32_16x16x32_bf16 v[140:143], v[96:99], v[184:187], v[140:143]
	v_mfma_f32_16x16x32_bf16 v[136:139], v[112:115], v[184:187], v[136:139]
	v_mfma_f32_16x16x32_bf16 v[120:123], v[112:115], v[210:213], v[120:123]
	v_mfma_f32_16x16x32_bf16 v[124:127], v[96:99], v[210:213], v[124:127]
	v_mfma_f32_16x16x32_bf16 v[92:95], v[96:99], v[218:221], v[92:95]
	v_mfma_f32_16x16x32_bf16 v[88:91], v[112:115], v[218:221], v[88:91]
	v_mfma_f32_16x16x32_bf16 v[72:75], v[112:115], v[226:229], v[72:75]
	v_mfma_f32_16x16x32_bf16 v[76:79], v[96:99], v[226:229], v[76:79]
	v_mfma_f32_16x16x32_bf16 v[140:143], v[108:111], v[188:191], v[140:143]
	v_mfma_f32_16x16x32_bf16 v[136:139], v[116:119], v[188:191], v[136:139]
	v_mfma_f32_16x16x32_bf16 v[120:123], v[116:119], v[214:217], v[120:123]
	v_mfma_f32_16x16x32_bf16 v[124:127], v[108:111], v[214:217], v[124:127]
	v_mfma_f32_16x16x32_bf16 v[92:95], v[108:111], v[222:225], v[92:95]
	v_mfma_f32_16x16x32_bf16 v[88:91], v[116:119], v[222:225], v[88:91]
	v_mfma_f32_16x16x32_bf16 v[72:75], v[116:119], v[230:233], v[72:75]
	v_mfma_f32_16x16x32_bf16 v[76:79], v[108:111], v[230:233], v[76:79]
	s_setprio 0
	s_setprio 1
	v_mfma_f32_16x16x32_bf16 v[132:135], v[162:165], v[184:187], v[132:135]
	v_mfma_f32_16x16x32_bf16 v[128:131], v[176:179], v[184:187], v[128:131]
	v_mfma_f32_16x16x32_bf16 v[100:103], v[176:179], v[210:213], v[100:103]
	v_mfma_f32_16x16x32_bf16 v[104:107], v[162:165], v[210:213], v[104:107]
	v_mfma_f32_16x16x32_bf16 v[84:87], v[162:165], v[218:221], v[84:87]
	v_mfma_f32_16x16x32_bf16 v[80:83], v[176:179], v[218:221], v[80:83]
	v_mfma_f32_16x16x32_bf16 v[64:67], v[176:179], v[226:229], v[64:67]
	v_mfma_f32_16x16x32_bf16 v[68:71], v[162:165], v[226:229], v[68:71]
	v_mfma_f32_16x16x32_bf16 v[132:135], v[166:169], v[188:191], v[132:135]
	v_mfma_f32_16x16x32_bf16 v[128:131], v[180:183], v[188:191], v[128:131]
	v_mfma_f32_16x16x32_bf16 v[100:103], v[180:183], v[214:217], v[100:103]
	v_mfma_f32_16x16x32_bf16 v[104:107], v[166:169], v[214:217], v[104:107]
	v_mfma_f32_16x16x32_bf16 v[84:87], v[166:169], v[222:225], v[84:87]
	v_mfma_f32_16x16x32_bf16 v[80:83], v[180:183], v[222:225], v[80:83]
	v_mfma_f32_16x16x32_bf16 v[64:67], v[180:183], v[230:233], v[64:67]
	v_mfma_f32_16x16x32_bf16 v[68:71], v[166:169], v[230:233], v[68:71]
	s_setprio 0
	s_barrier
	s_add_i32 s81, s81, s64
	v_lshl_add_u64 v[192:193], s[40:41], 0, v[150:151]
	s_mov_b32 m0, s81
	ds_read_b128 v[184:187], v174 offset:16384
	ds_read_b128 v[188:191], v174 offset:17408
	ds_read_b128 v[210:213], v174 offset:18432
	ds_read_b128 v[214:217], v174 offset:19456
	ds_read_b128 v[218:221], v174 offset:20480
	ds_read_b128 v[222:225], v174 offset:21504
	ds_read_b128 v[226:229], v174 offset:22528
	ds_read_b128 v[230:233], v174 offset:23552
	global_load_lds_dwordx4 v[192:193], off
	s_add_i32 m0, s81, 0x2000
	s_add_u32 s82, s40, 0x40000
	v_lshl_add_u64 v[234:235], s[40:41], 0, v[156:157]
	s_addc_u32 s83, s41, 0
	s_add_i32 s81, s84, s64
	global_load_lds_dwordx4 v[234:235], off
	v_lshl_add_u64 v[236:237], s[82:83], 0, v[150:151]
	s_mov_b32 m0, s81
	v_lshl_add_u64 v[238:239], s[42:43], 0, v[154:155]
	global_load_lds_dwordx4 v[236:237], off
	v_lshl_add_u64 v[236:237], s[82:83], 0, v[156:157]
	s_add_i32 m0, s81, 0x2000
	s_nop 0
	global_load_lds_dwordx4 v[236:237], off
	v_lshl_add_u64 v[236:237], s[42:43], 0, v[152:153]
	s_mov_b32 m0, s35
	s_nop 0
	global_load_lds_dwordx4 v[236:237], off
	s_mov_b32 m0, s65
	s_nop 0
	global_load_lds_dwordx4 v[238:239], off
	s_waitcnt vmcnt(8)
	s_waitcnt lgkmcnt(0)
	s_barrier
	s_setprio 1
	s_waitcnt lgkmcnt(0)
	v_mfma_f32_16x16x32_bf16 v[60:63], v[96:99], v[184:187], v[60:63]
	v_mfma_f32_16x16x32_bf16 v[56:59], v[112:115], v[184:187], v[56:59]
	v_mfma_f32_16x16x32_bf16 v[40:43], v[112:115], v[210:213], v[40:43]
	v_mfma_f32_16x16x32_bf16 v[48:51], v[96:99], v[210:213], v[48:51]
	v_mfma_f32_16x16x32_bf16 v[32:35], v[96:99], v[218:221], v[32:35]
	v_mfma_f32_16x16x32_bf16 v[24:27], v[112:115], v[218:221], v[24:27]
	v_mfma_f32_16x16x32_bf16 v[8:11], v[112:115], v[226:229], v[8:11]
	v_mfma_f32_16x16x32_bf16 v[16:19], v[96:99], v[226:229], v[16:19]
	v_mfma_f32_16x16x32_bf16 v[60:63], v[108:111], v[188:191], v[60:63]
	v_mfma_f32_16x16x32_bf16 v[56:59], v[116:119], v[188:191], v[56:59]
	v_mfma_f32_16x16x32_bf16 v[40:43], v[116:119], v[214:217], v[40:43]
	v_mfma_f32_16x16x32_bf16 v[48:51], v[108:111], v[214:217], v[48:51]
	v_mfma_f32_16x16x32_bf16 v[32:35], v[108:111], v[222:225], v[32:35]
	v_mfma_f32_16x16x32_bf16 v[24:27], v[116:119], v[222:225], v[24:27]
	v_mfma_f32_16x16x32_bf16 v[8:11], v[116:119], v[230:233], v[8:11]
	v_mfma_f32_16x16x32_bf16 v[16:19], v[108:111], v[230:233], v[16:19]
	s_setprio 0
	s_setprio 1
	v_mfma_f32_16x16x32_bf16 v[52:55], v[162:165], v[184:187], v[52:55]
	v_mfma_f32_16x16x32_bf16 v[44:47], v[176:179], v[184:187], v[44:47]
	v_mfma_f32_16x16x32_bf16 v[28:31], v[176:179], v[210:213], v[28:31]
	v_mfma_f32_16x16x32_bf16 v[36:39], v[162:165], v[210:213], v[36:39]
	v_mfma_f32_16x16x32_bf16 v[20:23], v[162:165], v[218:221], v[20:23]
	v_mfma_f32_16x16x32_bf16 v[12:15], v[176:179], v[218:221], v[12:15]
	v_mfma_f32_16x16x32_bf16 v[0:3], v[176:179], v[226:229], v[0:3]
	v_mfma_f32_16x16x32_bf16 v[4:7], v[162:165], v[226:229], v[4:7]
	v_mfma_f32_16x16x32_bf16 v[52:55], v[166:169], v[188:191], v[52:55]
	v_mfma_f32_16x16x32_bf16 v[44:47], v[180:183], v[188:191], v[44:47]
	v_mfma_f32_16x16x32_bf16 v[28:31], v[180:183], v[214:217], v[28:31]
	v_mfma_f32_16x16x32_bf16 v[36:39], v[166:169], v[214:217], v[36:39]
	v_mfma_f32_16x16x32_bf16 v[20:23], v[166:169], v[222:225], v[20:23]
	v_mfma_f32_16x16x32_bf16 v[12:15], v[180:183], v[222:225], v[12:15]
	v_mfma_f32_16x16x32_bf16 v[0:3], v[180:183], v[230:233], v[0:3]
	v_mfma_f32_16x16x32_bf16 v[4:7], v[166:169], v[230:233], v[4:7]
	s_setprio 0
	s_barrier
	s_add_i32 s81, 0, 0x18000
	s_add_i32 s82, 0, 0x1c000
	v_add_u32_e32 v116, s81, v171
	v_add_u32_e32 v175, s82, v171
	ds_read_b128 v[96:99], v116
	ds_read_b128 v[108:111], v116 offset:1024
	ds_read_b128 v[112:115], v116 offset:2048
	ds_read_b128 v[116:119], v116 offset:3072
	ds_read_b128 v[162:165], v175
	ds_read_b128 v[166:169], v175 offset:1024
	ds_read_b128 v[176:179], v175 offset:2048
	ds_read_b128 v[180:183], v175 offset:3072
	s_add_u32 s42, s42, 0x40000
	s_addc_u32 s43, s43, 0
	s_mov_b32 m0, s68
	v_lshl_add_u64 v[240:241], s[42:43], 0, v[152:153]
	ds_read_b128 v[184:187], v174 offset:32768
	ds_read_b128 v[188:191], v174 offset:33792
	ds_read_b128 v[210:213], v174 offset:34816
	ds_read_b128 v[214:217], v174 offset:35840
	ds_read_b128 v[218:221], v174 offset:36864
	ds_read_b128 v[222:225], v174 offset:37888
	ds_read_b128 v[226:229], v174 offset:38912
	ds_read_b128 v[230:233], v174 offset:39936
	global_load_lds_dwordx4 v[240:241], off
	v_lshl_add_u64 v[240:241], s[42:43], 0, v[154:155]
	s_mov_b32 m0, s69
	s_nop 0
	global_load_lds_dwordx4 v[240:241], off
	s_waitcnt vmcnt(8)
	s_waitcnt lgkmcnt(0)
	s_barrier
	s_setprio 1
	s_waitcnt lgkmcnt(0)
	v_mfma_f32_16x16x32_bf16 v[140:143], v[96:99], v[184:187], v[140:143]
	v_mfma_f32_16x16x32_bf16 v[136:139], v[112:115], v[184:187], v[136:139]
	v_mfma_f32_16x16x32_bf16 v[120:123], v[112:115], v[210:213], v[120:123]
	v_mfma_f32_16x16x32_bf16 v[124:127], v[96:99], v[210:213], v[124:127]
	v_mfma_f32_16x16x32_bf16 v[92:95], v[96:99], v[218:221], v[92:95]
	v_mfma_f32_16x16x32_bf16 v[88:91], v[112:115], v[218:221], v[88:91]
	v_mfma_f32_16x16x32_bf16 v[72:75], v[112:115], v[226:229], v[72:75]
	v_mfma_f32_16x16x32_bf16 v[76:79], v[96:99], v[226:229], v[76:79]
	v_mfma_f32_16x16x32_bf16 v[140:143], v[108:111], v[188:191], v[140:143]
	v_mfma_f32_16x16x32_bf16 v[136:139], v[116:119], v[188:191], v[136:139]
	v_mfma_f32_16x16x32_bf16 v[120:123], v[116:119], v[214:217], v[120:123]
	v_mfma_f32_16x16x32_bf16 v[124:127], v[108:111], v[214:217], v[124:127]
	v_mfma_f32_16x16x32_bf16 v[92:95], v[108:111], v[222:225], v[92:95]
	v_mfma_f32_16x16x32_bf16 v[88:91], v[116:119], v[222:225], v[88:91]
	v_mfma_f32_16x16x32_bf16 v[72:75], v[116:119], v[230:233], v[72:75]
	v_mfma_f32_16x16x32_bf16 v[76:79], v[108:111], v[230:233], v[76:79]
	s_setprio 0
	s_setprio 1
	v_mfma_f32_16x16x32_bf16 v[132:135], v[162:165], v[184:187], v[132:135]
	v_mfma_f32_16x16x32_bf16 v[128:131], v[176:179], v[184:187], v[128:131]
	v_mfma_f32_16x16x32_bf16 v[100:103], v[176:179], v[210:213], v[100:103]
	v_mfma_f32_16x16x32_bf16 v[104:107], v[162:165], v[210:213], v[104:107]
	v_mfma_f32_16x16x32_bf16 v[84:87], v[162:165], v[218:221], v[84:87]
	v_mfma_f32_16x16x32_bf16 v[80:83], v[176:179], v[218:221], v[80:83]
	v_mfma_f32_16x16x32_bf16 v[64:67], v[176:179], v[226:229], v[64:67]
	v_mfma_f32_16x16x32_bf16 v[68:71], v[162:165], v[226:229], v[68:71]
	v_mfma_f32_16x16x32_bf16 v[132:135], v[166:169], v[188:191], v[132:135]
	v_mfma_f32_16x16x32_bf16 v[128:131], v[180:183], v[188:191], v[128:131]
	v_mfma_f32_16x16x32_bf16 v[100:103], v[180:183], v[214:217], v[100:103]
	v_mfma_f32_16x16x32_bf16 v[104:107], v[166:169], v[214:217], v[104:107]
	v_mfma_f32_16x16x32_bf16 v[84:87], v[166:169], v[222:225], v[84:87]
	v_mfma_f32_16x16x32_bf16 v[80:83], v[180:183], v[222:225], v[80:83]
	v_mfma_f32_16x16x32_bf16 v[64:67], v[180:183], v[230:233], v[64:67]
	v_mfma_f32_16x16x32_bf16 v[68:71], v[166:169], v[230:233], v[68:71]
	s_setprio 0
	s_barrier
	s_add_i32 s42, s81, s64
	v_lshl_add_u64 v[192:193], v[192:193], 0, s[10:11]
	s_mov_b32 m0, s42
	ds_read_b128 v[184:187], v174 offset:49152
	ds_read_b128 v[188:191], v174 offset:50176
	ds_read_b128 v[210:213], v174 offset:51200
	ds_read_b128 v[214:217], v174 offset:52224
	ds_read_b128 v[218:221], v174 offset:53248
	ds_read_b128 v[222:225], v174 offset:54272
	ds_read_b128 v[226:229], v174 offset:55296
	ds_read_b128 v[230:233], v174 offset:56320
	global_load_lds_dwordx4 v[192:193], off
	s_add_i32 m0, s42, 0x2000
	s_add_u32 s40, s40, 0x40080
	v_lshl_add_u64 v[192:193], v[234:235], 0, s[10:11]
	s_addc_u32 s41, s41, 0
	s_add_i32 s42, s82, s64
	global_load_lds_dwordx4 v[192:193], off
	v_lshl_add_u64 v[192:193], s[40:41], 0, v[150:151]
	s_mov_b32 m0, s42
	s_nop 0
	global_load_lds_dwordx4 v[192:193], off
	v_lshl_add_u64 v[192:193], s[40:41], 0, v[156:157]
	s_add_i32 m0, s42, 0x2000
	s_nop 0
	global_load_lds_dwordx4 v[192:193], off
	v_lshl_add_u64 v[192:193], v[236:237], 0, s[10:11]
	s_mov_b32 m0, s70
	s_nop 0
	global_load_lds_dwordx4 v[192:193], off
	v_lshl_add_u64 v[192:193], v[238:239], 0, s[10:11]
	s_mov_b32 m0, s71
	s_nop 0
	global_load_lds_dwordx4 v[192:193], off
	s_waitcnt vmcnt(8)
	s_waitcnt lgkmcnt(0)
	s_barrier
	s_setprio 1
	s_waitcnt lgkmcnt(0)
	v_mfma_f32_16x16x32_bf16 v[60:63], v[96:99], v[184:187], v[60:63]
	v_mfma_f32_16x16x32_bf16 v[56:59], v[112:115], v[184:187], v[56:59]
	v_mfma_f32_16x16x32_bf16 v[40:43], v[112:115], v[210:213], v[40:43]
	v_mfma_f32_16x16x32_bf16 v[48:51], v[96:99], v[210:213], v[48:51]
	v_mfma_f32_16x16x32_bf16 v[32:35], v[96:99], v[218:221], v[32:35]
	v_mfma_f32_16x16x32_bf16 v[24:27], v[112:115], v[218:221], v[24:27]
	v_mfma_f32_16x16x32_bf16 v[8:11], v[112:115], v[226:229], v[8:11]
	v_mfma_f32_16x16x32_bf16 v[16:19], v[96:99], v[226:229], v[16:19]
	v_mfma_f32_16x16x32_bf16 v[60:63], v[108:111], v[188:191], v[60:63]
	v_mfma_f32_16x16x32_bf16 v[56:59], v[116:119], v[188:191], v[56:59]
	v_mfma_f32_16x16x32_bf16 v[40:43], v[116:119], v[214:217], v[40:43]
	v_mfma_f32_16x16x32_bf16 v[48:51], v[108:111], v[214:217], v[48:51]
	v_mfma_f32_16x16x32_bf16 v[32:35], v[108:111], v[222:225], v[32:35]
	v_mfma_f32_16x16x32_bf16 v[24:27], v[116:119], v[222:225], v[24:27]
	v_mfma_f32_16x16x32_bf16 v[8:11], v[116:119], v[230:233], v[8:11]
	v_mfma_f32_16x16x32_bf16 v[16:19], v[108:111], v[230:233], v[16:19]
	s_setprio 0
	s_setprio 1
	v_mfma_f32_16x16x32_bf16 v[52:55], v[162:165], v[184:187], v[52:55]
	v_mfma_f32_16x16x32_bf16 v[44:47], v[176:179], v[184:187], v[44:47]
	v_mfma_f32_16x16x32_bf16 v[28:31], v[176:179], v[210:213], v[28:31]
	v_mfma_f32_16x16x32_bf16 v[36:39], v[162:165], v[210:213], v[36:39]
	v_mfma_f32_16x16x32_bf16 v[20:23], v[162:165], v[218:221], v[20:23]
	v_mfma_f32_16x16x32_bf16 v[12:15], v[176:179], v[218:221], v[12:15]
	v_mfma_f32_16x16x32_bf16 v[0:3], v[176:179], v[226:229], v[0:3]
	v_mfma_f32_16x16x32_bf16 v[4:7], v[162:165], v[226:229], v[4:7]
	v_mfma_f32_16x16x32_bf16 v[52:55], v[166:169], v[188:191], v[52:55]
	v_mfma_f32_16x16x32_bf16 v[44:47], v[180:183], v[188:191], v[44:47]
	v_mfma_f32_16x16x32_bf16 v[28:31], v[180:183], v[214:217], v[28:31]
	v_mfma_f32_16x16x32_bf16 v[36:39], v[166:169], v[214:217], v[36:39]
	v_mfma_f32_16x16x32_bf16 v[20:23], v[166:169], v[222:225], v[20:23]
	v_mfma_f32_16x16x32_bf16 v[12:15], v[180:183], v[222:225], v[12:15]
	v_mfma_f32_16x16x32_bf16 v[0:3], v[180:183], v[230:233], v[0:3]
	v_mfma_f32_16x16x32_bf16 v[4:7], v[166:169], v[230:233], v[4:7]
	s_setprio 0
	s_barrier
	s_add_i32 s80, s80, 2
	s_add_u32 s78, s78, 0x100
	s_addc_u32 s79, s79, 0
	s_add_u32 s38, s38, 0x100
	s_addc_u32 s39, s39, 0
	s_cmp_gt_u32 s80, 13
	s_cbranch_scc0 .LBB0_339
	s_and_b64 vcc, exec, s[16:17]
	s_cbranch_vccz .LBB0_342
	s_barrier

.LBB0_616:
	s_add_i32 vcc_lo, s46, 2
	s_add_u32 s86, s24, 0x80
	s_addc_u32 s47, s25, 0
	s_add_i32 vcc_hi, 0, 0x10000
	s_cmp_eq_u32 s71, s46
	s_cselect_b32 s47, s5, s47
	s_cselect_b32 s46, s4, s86
	s_cselect_b32 s87, s7, s85
	s_cselect_b32 s86, s6, s20
	s_add_i32 s88, 0, 0x14000
	v_add_u32_e32 v60, vcc_hi, v211
	v_add_u32_e32 v159, s88, v211
	ds_read_b128 v[40:43], v60
	ds_read_b128 v[44:47], v60 offset:1024
	ds_read_b128 v[52:55], v60 offset:2048
	ds_read_b128 v[60:63], v60 offset:3072
	ds_read_b128 v[168:171], v159
	ds_read_b128 v[172:175], v159 offset:1024
	ds_read_b128 v[176:179], v159 offset:2048
	ds_read_b128 v[180:183], v159 offset:3072
	v_lshl_add_u64 v[192:193], s[24:25], 0, v[166:167]
	s_add_i32 m0, s65, 0xc000
	ds_read_b128 v[184:187], v213
	ds_read_b128 v[188:191], v213 offset:1024
	ds_read_b128 v[214:217], v213 offset:2048
	ds_read_b128 v[218:221], v213 offset:3072
	ds_read_b128 v[222:225], v213 offset:4096
	ds_read_b128 v[226:229], v213 offset:5120
	ds_read_b128 v[230:233], v213 offset:6144
	ds_read_b128 v[234:237], v213 offset:7168
	global_load_lds_dwordx4 v[192:193], off
	v_lshl_add_u64 v[192:193], s[24:25], 0, v[164:165]
	s_add_i32 m0, s65, 0xe000
	s_nop 0
	global_load_lds_dwordx4 v[192:193], off
	s_waitcnt vmcnt(8)
	s_waitcnt lgkmcnt(0)
	s_barrier
	s_setprio 1
	s_waitcnt lgkmcnt(0)
	v_mfma_f32_16x16x32_bf16 v[140:143], v[40:43], v[184:187], v[140:143]
	v_mfma_f32_16x16x32_bf16 v[136:139], v[52:55], v[184:187], v[136:139]
	v_mfma_f32_16x16x32_bf16 v[120:123], v[52:55], v[214:217], v[120:123]
	v_mfma_f32_16x16x32_bf16 v[124:127], v[40:43], v[214:217], v[124:127]
	v_mfma_f32_16x16x32_bf16 v[108:111], v[40:43], v[222:225], v[108:111]
	v_mfma_f32_16x16x32_bf16 v[104:107], v[52:55], v[222:225], v[104:107]
	v_mfma_f32_16x16x32_bf16 v[88:91], v[52:55], v[230:233], v[88:91]
	v_mfma_f32_16x16x32_bf16 v[92:95], v[40:43], v[230:233], v[92:95]
	v_mfma_f32_16x16x32_bf16 v[140:143], v[44:47], v[188:191], v[140:143]
	v_mfma_f32_16x16x32_bf16 v[136:139], v[60:63], v[188:191], v[136:139]
	v_mfma_f32_16x16x32_bf16 v[120:123], v[60:63], v[218:221], v[120:123]
	v_mfma_f32_16x16x32_bf16 v[124:127], v[44:47], v[218:221], v[124:127]
	v_mfma_f32_16x16x32_bf16 v[108:111], v[44:47], v[226:229], v[108:111]
	v_mfma_f32_16x16x32_bf16 v[104:107], v[60:63], v[226:229], v[104:107]
	v_mfma_f32_16x16x32_bf16 v[88:91], v[60:63], v[234:237], v[88:91]
	v_mfma_f32_16x16x32_bf16 v[92:95], v[44:47], v[234:237], v[92:95]
	s_setprio 0
	s_setprio 1
	v_mfma_f32_16x16x32_bf16 v[132:135], v[168:171], v[184:187], v[132:135]
	v_mfma_f32_16x16x32_bf16 v[128:131], v[176:179], v[184:187], v[128:131]
	v_mfma_f32_16x16x32_bf16 v[112:115], v[176:179], v[214:217], v[112:115]
	v_mfma_f32_16x16x32_bf16 v[116:119], v[168:171], v[214:217], v[116:119]
	v_mfma_f32_16x16x32_bf16 v[100:103], v[168:171], v[222:225], v[100:103]
	v_mfma_f32_16x16x32_bf16 v[96:99], v[176:179], v[222:225], v[96:99]
	v_mfma_f32_16x16x32_bf16 v[80:83], v[176:179], v[230:233], v[80:83]
	v_mfma_f32_16x16x32_bf16 v[84:87], v[168:171], v[230:233], v[84:87]
	v_mfma_f32_16x16x32_bf16 v[132:135], v[172:175], v[188:191], v[132:135]
	v_mfma_f32_16x16x32_bf16 v[128:131], v[180:183], v[188:191], v[128:131]
	v_mfma_f32_16x16x32_bf16 v[112:115], v[180:183], v[218:221], v[112:115]
	v_mfma_f32_16x16x32_bf16 v[116:119], v[172:175], v[218:221], v[116:119]
	v_mfma_f32_16x16x32_bf16 v[100:103], v[172:175], v[226:229], v[100:103]
	v_mfma_f32_16x16x32_bf16 v[96:99], v[180:183], v[226:229], v[96:99]
	v_mfma_f32_16x16x32_bf16 v[80:83], v[180:183], v[234:237], v[80:83]
	v_mfma_f32_16x16x32_bf16 v[84:87], v[172:175], v[234:237], v[84:87]
	s_setprio 0
	s_barrier
	s_add_i32 s89, vcc_hi, s64
	v_lshl_add_u64 v[192:193], s[86:87], 0, v[150:151]
	s_mov_b32 m0, s89
	ds_read_b128 v[184:187], v213 offset:16384
	ds_read_b128 v[188:191], v213 offset:17408
	ds_read_b128 v[214:217], v213 offset:18432
	ds_read_b128 v[218:221], v213 offset:19456
	ds_read_b128 v[222:225], v213 offset:20480
	ds_read_b128 v[226:229], v213 offset:21504
	ds_read_b128 v[230:233], v213 offset:22528
	ds_read_b128 v[234:237], v213 offset:23552
	global_load_lds_dwordx4 v[192:193], off
	s_add_i32 m0, s89, 0x2000
	v_lshl_add_u64 v[238:239], s[86:87], 0, v[156:157]
	s_add_u32 s86, s86, s38
	s_addc_u32 s87, s87, 0
	s_add_i32 s88, s88, s64
	global_load_lds_dwordx4 v[238:239], off
	v_lshl_add_u64 v[240:241], s[86:87], 0, v[150:151]
	s_mov_b32 m0, s88
	v_lshl_add_u64 v[242:243], s[86:87], 0, v[156:157]
	global_load_lds_dwordx4 v[240:241], off
	s_add_i32 m0, s88, 0x2000
	v_lshl_add_u64 v[244:245], s[46:47], 0, v[152:153]
	global_load_lds_dwordx4 v[242:243], off
	s_mov_b32 m0, s65
	v_lshl_add_u64 v[246:247], s[46:47], 0, v[154:155]
	global_load_lds_dwordx4 v[244:245], off
	s_mov_b32 m0, s57
	s_nop 0
	global_load_lds_dwordx4 v[246:247], off
	s_waitcnt vmcnt(8)
	s_waitcnt lgkmcnt(0)
	s_barrier
	s_setprio 1
	s_waitcnt lgkmcnt(0)
	v_mfma_f32_16x16x32_bf16 v[76:79], v[40:43], v[184:187], v[76:79]
	v_mfma_f32_16x16x32_bf16 v[72:75], v[52:55], v[184:187], v[72:75]
	v_mfma_f32_16x16x32_bf16 v[48:51], v[52:55], v[214:217], v[48:51]
	v_mfma_f32_16x16x32_bf16 v[56:59], v[40:43], v[214:217], v[56:59]
	v_mfma_f32_16x16x32_bf16 v[28:31], v[40:43], v[222:225], v[28:31]
	v_mfma_f32_16x16x32_bf16 v[24:27], v[52:55], v[222:225], v[24:27]
	v_mfma_f32_16x16x32_bf16 v[8:11], v[52:55], v[230:233], v[8:11]
	v_mfma_f32_16x16x32_bf16 v[12:15], v[40:43], v[230:233], v[12:15]
	v_mfma_f32_16x16x32_bf16 v[76:79], v[44:47], v[188:191], v[76:79]
	v_mfma_f32_16x16x32_bf16 v[72:75], v[60:63], v[188:191], v[72:75]
	v_mfma_f32_16x16x32_bf16 v[48:51], v[60:63], v[218:221], v[48:51]
	v_mfma_f32_16x16x32_bf16 v[56:59], v[44:47], v[218:221], v[56:59]
	v_mfma_f32_16x16x32_bf16 v[28:31], v[44:47], v[226:229], v[28:31]
	v_mfma_f32_16x16x32_bf16 v[24:27], v[60:63], v[226:229], v[24:27]
	v_mfma_f32_16x16x32_bf16 v[8:11], v[60:63], v[234:237], v[8:11]
	v_mfma_f32_16x16x32_bf16 v[12:15], v[44:47], v[234:237], v[12:15]
	s_setprio 0
	s_setprio 1
	v_mfma_f32_16x16x32_bf16 v[36:39], v[168:171], v[214:217], v[36:39]
	v_mfma_f32_16x16x32_bf16 v[32:35], v[176:179], v[214:217], v[32:35]
	v_mfma_f32_16x16x32_bf16 v[20:23], v[168:171], v[222:225], v[20:23]
	v_mfma_f32_16x16x32_bf16 v[16:19], v[176:179], v[222:225], v[16:19]
	v_mfma_f32_16x16x32_bf16 v[4:7], v[168:171], v[230:233], v[4:7]
	v_mfma_f32_16x16x32_bf16 v[0:3], v[176:179], v[230:233], v[0:3]
	v_mfma_f32_16x16x32_bf16 v[40:43], v[168:171], v[184:187], v[68:71]
	v_mfma_f32_16x16x32_bf16 v[44:47], v[176:179], v[184:187], v[64:67]
	v_mfma_f32_16x16x32_bf16 v[36:39], v[172:175], v[218:221], v[36:39]
	v_mfma_f32_16x16x32_bf16 v[32:35], v[180:183], v[218:221], v[32:35]
	v_mfma_f32_16x16x32_bf16 v[16:19], v[180:183], v[226:229], v[16:19]
	v_mfma_f32_16x16x32_bf16 v[20:23], v[172:175], v[226:229], v[20:23]
	v_mfma_f32_16x16x32_bf16 v[4:7], v[172:175], v[234:237], v[4:7]
	v_mfma_f32_16x16x32_bf16 v[0:3], v[180:183], v[234:237], v[0:3]
	v_mfma_f32_16x16x32_bf16 v[44:47], v[180:183], v[188:191], v[44:47]
	v_mfma_f32_16x16x32_bf16 v[40:43], v[172:175], v[188:191], v[40:43]
	s_setprio 0
	s_barrier
	s_add_i32 s86, 0, 0x18000
	s_add_i32 s87, 0, 0x1c000
	v_add_u32_e32 v68, s86, v211
	v_add_u32_e32 v159, s87, v211
	ds_read_b128 v[52:55], v68
	ds_read_b128 v[60:63], v68 offset:1024
	ds_read_b128 v[64:67], v68 offset:2048
	ds_read_b128 v[68:71], v68 offset:3072
	ds_read_b128 v[168:171], v159
	ds_read_b128 v[172:175], v159 offset:1024
	ds_read_b128 v[176:179], v159 offset:2048
	ds_read_b128 v[180:183], v159 offset:3072
	s_add_u32 s46, s46, s38
	s_addc_u32 s47, s47, 0
	s_mov_b32 m0, s68
	v_lshl_add_u64 v[248:249], s[46:47], 0, v[152:153]
	ds_read_b128 v[184:187], v213 offset:32768
	ds_read_b128 v[188:191], v213 offset:33792
	ds_read_b128 v[214:217], v213 offset:34816
	ds_read_b128 v[218:221], v213 offset:35840
	ds_read_b128 v[222:225], v213 offset:36864
	ds_read_b128 v[226:229], v213 offset:37888
	ds_read_b128 v[230:233], v213 offset:38912
	ds_read_b128 v[234:237], v213 offset:39936
	global_load_lds_dwordx4 v[248:249], off
	v_lshl_add_u64 v[248:249], s[46:47], 0, v[154:155]
	s_mov_b32 m0, s69
	s_nop 0
	global_load_lds_dwordx4 v[248:249], off
	s_waitcnt vmcnt(8)
	s_waitcnt lgkmcnt(0)
	s_barrier
	s_setprio 1
	s_waitcnt lgkmcnt(0)
	v_mfma_f32_16x16x32_bf16 v[140:143], v[52:55], v[184:187], v[140:143]
	v_mfma_f32_16x16x32_bf16 v[136:139], v[64:67], v[184:187], v[136:139]
	v_mfma_f32_16x16x32_bf16 v[120:123], v[64:67], v[214:217], v[120:123]
	v_mfma_f32_16x16x32_bf16 v[124:127], v[52:55], v[214:217], v[124:127]
	v_mfma_f32_16x16x32_bf16 v[108:111], v[52:55], v[222:225], v[108:111]
	v_mfma_f32_16x16x32_bf16 v[104:107], v[64:67], v[222:225], v[104:107]
	v_mfma_f32_16x16x32_bf16 v[88:91], v[64:67], v[230:233], v[88:91]
	v_mfma_f32_16x16x32_bf16 v[92:95], v[52:55], v[230:233], v[92:95]
	v_mfma_f32_16x16x32_bf16 v[140:143], v[60:63], v[188:191], v[140:143]
	v_mfma_f32_16x16x32_bf16 v[136:139], v[68:71], v[188:191], v[136:139]
	v_mfma_f32_16x16x32_bf16 v[120:123], v[68:71], v[218:221], v[120:123]
	v_mfma_f32_16x16x32_bf16 v[124:127], v[60:63], v[218:221], v[124:127]
	v_mfma_f32_16x16x32_bf16 v[108:111], v[60:63], v[226:229], v[108:111]
	v_mfma_f32_16x16x32_bf16 v[104:107], v[68:71], v[226:229], v[104:107]
	v_mfma_f32_16x16x32_bf16 v[88:91], v[68:71], v[234:237], v[88:91]
	v_mfma_f32_16x16x32_bf16 v[92:95], v[60:63], v[234:237], v[92:95]
	s_setprio 0
	s_setprio 1
	v_mfma_f32_16x16x32_bf16 v[132:135], v[168:171], v[184:187], v[132:135]
	v_mfma_f32_16x16x32_bf16 v[128:131], v[176:179], v[184:187], v[128:131]
	v_mfma_f32_16x16x32_bf16 v[112:115], v[176:179], v[214:217], v[112:115]
	v_mfma_f32_16x16x32_bf16 v[116:119], v[168:171], v[214:217], v[116:119]
	v_mfma_f32_16x16x32_bf16 v[100:103], v[168:171], v[222:225], v[100:103]
	v_mfma_f32_16x16x32_bf16 v[96:99], v[176:179], v[222:225], v[96:99]
	v_mfma_f32_16x16x32_bf16 v[80:83], v[176:179], v[230:233], v[80:83]
	v_mfma_f32_16x16x32_bf16 v[84:87], v[168:171], v[230:233], v[84:87]
	v_mfma_f32_16x16x32_bf16 v[132:135], v[172:175], v[188:191], v[132:135]
	v_mfma_f32_16x16x32_bf16 v[128:131], v[180:183], v[188:191], v[128:131]
	v_mfma_f32_16x16x32_bf16 v[112:115], v[180:183], v[218:221], v[112:115]
	v_mfma_f32_16x16x32_bf16 v[116:119], v[172:175], v[218:221], v[116:119]
	v_mfma_f32_16x16x32_bf16 v[100:103], v[172:175], v[226:229], v[100:103]
	v_mfma_f32_16x16x32_bf16 v[96:99], v[180:183], v[226:229], v[96:99]
	v_mfma_f32_16x16x32_bf16 v[80:83], v[180:183], v[234:237], v[80:83]
	v_mfma_f32_16x16x32_bf16 v[84:87], v[172:175], v[234:237], v[84:87]
	s_setprio 0
	s_barrier
	s_add_i32 s46, s86, s64
	v_lshl_add_u64 v[192:193], v[192:193], 0, s[10:11]
	s_mov_b32 m0, s46
	ds_read_b128 v[184:187], v213 offset:49152
	ds_read_b128 v[188:191], v213 offset:50176
	ds_read_b128 v[214:217], v213 offset:51200
	ds_read_b128 v[218:221], v213 offset:52224
	ds_read_b128 v[222:225], v213 offset:53248
	ds_read_b128 v[226:229], v213 offset:54272
	ds_read_b128 v[230:233], v213 offset:55296
	ds_read_b128 v[234:237], v213 offset:56320
	global_load_lds_dwordx4 v[192:193], off
	v_lshl_add_u64 v[192:193], v[238:239], 0, s[10:11]
	s_add_i32 m0, s46, 0x2000
	s_add_i32 s46, s87, s64
	global_load_lds_dwordx4 v[192:193], off
	v_lshl_add_u64 v[192:193], v[240:241], 0, s[10:11]
	s_mov_b32 m0, s46
	s_nop 0
	global_load_lds_dwordx4 v[192:193], off
	v_lshl_add_u64 v[192:193], v[242:243], 0, s[10:11]
	s_add_i32 m0, s46, 0x2000
	s_nop 0
	global_load_lds_dwordx4 v[192:193], off
	v_lshl_add_u64 v[192:193], v[244:245], 0, s[10:11]
	s_mov_b32 m0, s72
	s_nop 0
	global_load_lds_dwordx4 v[192:193], off
	v_lshl_add_u64 v[192:193], v[246:247], 0, s[10:11]
	s_mov_b32 m0, s73
	s_nop 0
	global_load_lds_dwordx4 v[192:193], off
	s_waitcnt vmcnt(8)
	s_waitcnt lgkmcnt(0)
	s_barrier
	s_setprio 1
	s_waitcnt lgkmcnt(0)
	v_mfma_f32_16x16x32_bf16 v[76:79], v[52:55], v[184:187], v[76:79]
	v_mfma_f32_16x16x32_bf16 v[72:75], v[64:67], v[184:187], v[72:75]
	v_mfma_f32_16x16x32_bf16 v[48:51], v[64:67], v[214:217], v[48:51]
	v_mfma_f32_16x16x32_bf16 v[56:59], v[52:55], v[214:217], v[56:59]
	v_mfma_f32_16x16x32_bf16 v[28:31], v[52:55], v[222:225], v[28:31]
	v_mfma_f32_16x16x32_bf16 v[24:27], v[64:67], v[222:225], v[24:27]
	v_mfma_f32_16x16x32_bf16 v[8:11], v[64:67], v[230:233], v[8:11]
	v_mfma_f32_16x16x32_bf16 v[12:15], v[52:55], v[230:233], v[12:15]
	v_mfma_f32_16x16x32_bf16 v[76:79], v[60:63], v[188:191], v[76:79]
	v_mfma_f32_16x16x32_bf16 v[72:75], v[68:71], v[188:191], v[72:75]
	v_mfma_f32_16x16x32_bf16 v[48:51], v[68:71], v[218:221], v[48:51]
	v_mfma_f32_16x16x32_bf16 v[56:59], v[60:63], v[218:221], v[56:59]
	v_mfma_f32_16x16x32_bf16 v[28:31], v[60:63], v[226:229], v[28:31]
	v_mfma_f32_16x16x32_bf16 v[24:27], v[68:71], v[226:229], v[24:27]
	v_mfma_f32_16x16x32_bf16 v[8:11], v[68:71], v[234:237], v[8:11]
	v_mfma_f32_16x16x32_bf16 v[12:15], v[60:63], v[234:237], v[12:15]
	s_setprio 0
	s_setprio 1
	v_mfma_f32_16x16x32_bf16 v[40:43], v[168:171], v[184:187], v[40:43]
	v_mfma_f32_16x16x32_bf16 v[68:71], v[172:175], v[188:191], v[40:43]
	v_mfma_f32_16x16x32_bf16 v[40:43], v[176:179], v[184:187], v[44:47]
	v_mfma_f32_16x16x32_bf16 v[36:39], v[168:171], v[214:217], v[36:39]
	v_mfma_f32_16x16x32_bf16 v[32:35], v[176:179], v[214:217], v[32:35]
	v_mfma_f32_16x16x32_bf16 v[20:23], v[168:171], v[222:225], v[20:23]
	v_mfma_f32_16x16x32_bf16 v[16:19], v[176:179], v[222:225], v[16:19]
	v_mfma_f32_16x16x32_bf16 v[4:7], v[168:171], v[230:233], v[4:7]
	v_mfma_f32_16x16x32_bf16 v[0:3], v[176:179], v[230:233], v[0:3]
	v_mfma_f32_16x16x32_bf16 v[64:67], v[180:183], v[188:191], v[40:43]
	v_mfma_f32_16x16x32_bf16 v[36:39], v[172:175], v[218:221], v[36:39]
	v_mfma_f32_16x16x32_bf16 v[32:35], v[180:183], v[218:221], v[32:35]
	v_mfma_f32_16x16x32_bf16 v[20:23], v[172:175], v[226:229], v[20:23]
	v_mfma_f32_16x16x32_bf16 v[16:19], v[180:183], v[226:229], v[16:19]
	v_mfma_f32_16x16x32_bf16 v[4:7], v[172:175], v[234:237], v[4:7]
	v_mfma_f32_16x16x32_bf16 v[0:3], v[180:183], v[234:237], v[0:3]
	s_setprio 0
	s_barrier
	s_add_u32 s20, s20, 0x100
	s_addc_u32 s85, s85, 0
	s_add_u32 s24, s24, 0x100
	s_addc_u32 s25, s25, 0
	s_cmp_ge_u32 vcc_lo, s74
	s_mov_b32 s46, vcc_lo
	s_cbranch_scc0 .LBB0_616
	s_and_b64 vcc, exec, s[16:17]
	s_cbranch_vccz .LBB0_619
	s_barrier
